# transposed rmsnorm phase: 16-token work items (384 items over all CUs) instead of 32-token items
# speedup vs baseline: 1.1922x; 1.0068x over previous
.LBB0_1400:
	s_andn2_b64 vcc, exec, s[4:5]
	s_cbranch_vccnz .LBB0_1409
	v_readlane_b32 s4, v242, 0
	s_nop 0
	v_mov_b32_e32 v123, v127
	s_cmpk_gt_u32 s4, 0x17f
	s_cbranch_scc1 .LBB0_1409
	s_load_dwordx2 s[4:5], s[72:73], 0x50
	v_readlane_b32 s7, v239, 60
	s_mul_i32 s6, s7, 0x3000
	s_waitcnt vmcnt(7)
	v_and_b32_e32 v17, 63, v123
	v_mov_b32_e32 v113, v125
	s_waitcnt lgkmcnt(0)
	s_add_u32 s4, s4, s6
	v_lshlrev_b32_e32 v112, 4, v17
	s_addc_u32 s5, s5, 0
	v_lshl_add_u64 v[0:1], s[4:5], 0, v[112:113]
	v_add_co_u32_e32 v8, vcc, s77, v0
	v_lshl_add_u64 v[12:13], v[0:1], 0, s[22:23]
	s_nop 0
	v_addc_co_u32_e32 v9, vcc, 0, v1, vcc
	global_load_dwordx4 v[0:3], v[12:13], off offset:1024
	global_load_dwordx4 v[4:7], v[12:13], off offset:2048
	s_nop 0
	global_load_dwordx4 v[8:11], v[8:9], off
	s_nop 0
	global_load_dwordx4 v[12:15], v[12:13], off offset:3072
	s_mul_i32 s4, s7, 0x1b000
	s_add_u32 s6, s0, s4
	v_readlane_b32 s4, v239, 61
	s_addc_u32 s7, s1, 0
	v_readlane_b32 s5, v239, 62
	s_and_b64 s[4:5], s[4:5], exec
	s_mov_b32 s4, 0x68f6000
	s_cselect_b32 s4, 0x10eba000, s4
	s_add_u32 s6, s6, 0x3000
	s_addc_u32 s7, s7, 0
	s_add_u32 s14, s0, s4
	v_add_u32_e32 v19, 0x100, v123
	s_movk_i32 s0, 0x200
	v_ashrrev_i32_e32 v18, 6, v123
	s_addc_u32 s15, s1, 0
	v_and_b32_e32 v116, 0x3ff, v19
	v_bitop3_b32 v118, v123, s0, v177 bitop3:0x6c
	v_add_u32_e32 v19, 0x300, v123
	s_movk_i32 s0, 0x804
	v_lshlrev_b32_e32 v16, 2, v17
	s_add_u32 s16, s16, 0xff000000
	v_and_b32_e32 v114, 0x3ff, v123
	v_and_b32_e32 v120, 0x3ff, v19
	v_mul_lo_u32 v19, v18, s0
	v_readlane_b32 s18, v239, 29
	v_cmp_gt_i32_e32 vcc, 32, v18
	s_addc_u32 s17, s17, -1
	v_lshlrev_b32_e32 v122, 1, v114
	v_mov_b32_e32 v115, v125
	v_lshlrev_b32_e32 v130, 1, v116
	v_mov_b32_e32 v117, v125
	v_lshlrev_b32_e32 v132, 1, v118
	v_mov_b32_e32 v119, v125
	v_lshlrev_b32_e32 v134, 1, v120
	v_mov_b32_e32 v121, v125
	v_add_u32_e32 v113, -8, v18
	v_lshl_add_u32 v129, v17, 3, v19
	v_add_u32_e32 v136, s18, v18
	v_lshlrev_b32_e32 v138, 2, v16
	v_readlane_b32 s19, v242, 0
	s_mov_b32 s20, 0x3a800000

.LBB0_1405:
	s_waitcnt vmcnt(9)
	v_add_u32_e32 v24, s18, v133
	v_add_u32_e32 v18, 0xfffff008, v24
	v_add_u32_e32 v25, 8, v24
	v_lshrrev_b32_e32 v18, 10, v18
	v_cmp_gt_i32_e64 s[0:1], s77, v25
	v_mad_u32_u24 v18, v18, s92, s92
	v_mov_b32_e32 v139, v125
	v_cndmask_b32_e64 v124, v18, 0, s[0:1]
	v_lshl_add_u64 v[18:19], v[124:125], 2, s[6:7]
	v_mov_b32_e32 v26, s17
	v_mov_b32_e32 v27, s12
	s_waitcnt vmcnt(8)
	v_mov_b32_e32 v28, s16
	v_mov_b32_e32 v29, s13
	v_lshl_add_u64 v[18:19], v[18:19], 0, v[138:139]
	v_cndmask_b32_e64 v17, v26, v27, s[0:1]
	v_cndmask_b32_e64 v16, v28, v29, s[0:1]
	v_add_co_u32_e64 v22, s[0:1], s77, v18
	v_lshl_add_u64 v[16:17], v[16:17], 0, v[140:141]
	s_nop 0
	v_addc_co_u32_e64 v23, s[0:1], 0, v19, s[0:1]
	v_lshl_add_u64 v[20:21], v[18:19], 0, s[22:23]
	global_load_dwordx4 v[92:95], v[16:17], off
	global_load_dwordx4 v[88:91], v[18:19], off
	global_load_dwordx4 v[96:99], v[22:23], off
	global_load_dwordx4 v[84:87], v[16:17], off offset:1024
	global_load_dwordx4 v[80:83], v[18:19], off offset:1024
	global_load_dwordx4 v[100:103], v[20:21], off offset:1024
	global_load_dwordx4 v[76:79], v[16:17], off offset:2048
	global_load_dwordx4 v[72:75], v[18:19], off offset:2048
	global_load_dwordx4 v[104:107], v[20:21], off offset:2048
	global_load_dwordx4 v[56:59], v[16:17], off offset:3072
	global_load_dwordx4 v[52:55], v[18:19], off offset:3072
	global_load_dwordx4 v[108:111], v[20:21], off offset:3072
	v_add_u32_e32 v16, 12, v24
	s_movk_i32 s0, 0xffc
	v_cmp_gt_i32_e64 s[0:1], s0, v25
	v_ashrrev_i32_e32 v17, 31, v16
	v_lshlrev_b64 v[16:17], 12, v[16:17]
	v_cndmask_b32_e64 v19, v26, v27, s[0:1]
	v_cndmask_b32_e64 v18, v28, v29, s[0:1]
	v_lshl_add_u64 v[16:17], v[18:19], 0, v[16:17]
	v_add_u32_e32 v18, 0xfffff00c, v24
	v_lshrrev_b32_e32 v18, 10, v18
	v_mad_u32_u24 v18, v18, s92, s92
	v_cndmask_b32_e64 v124, v18, 0, s[0:1]
	v_lshl_add_u64 v[18:19], v[124:125], 2, s[6:7]
	v_lshl_add_u64 v[18:19], v[18:19], 0, v[138:139]
	v_add_co_u32_e64 v22, s[0:1], s77, v18
	v_lshl_add_u64 v[16:17], v[16:17], 0, v[138:139]
	v_lshl_add_u64 v[20:21], v[18:19], 0, s[22:23]
	v_addc_co_u32_e64 v23, s[0:1], 0, v19, s[0:1]
	global_load_dwordx4 v[64:67], v[16:17], off
	global_load_dwordx4 v[60:63], v[18:19], off
	global_load_dwordx4 v[68:71], v[22:23], off
	global_load_dwordx4 v[48:51], v[16:17], off offset:1024
	global_load_dwordx4 v[40:43], v[18:19], off offset:1024
	global_load_dwordx4 v[44:47], v[20:21], off offset:1024
	global_load_dwordx4 v[36:39], v[16:17], off offset:2048
	global_load_dwordx4 v[28:31], v[18:19], off offset:2048
	global_load_dwordx4 v[32:35], v[20:21], off offset:2048
	global_load_dwordx4 v[24:27], v[16:17], off offset:3072
	s_nop 0
	global_load_dwordx4 v[16:19], v[18:19], off offset:3072
	s_nop 0
	global_load_dwordx4 v[20:23], v[20:21], off offset:3072
	v_and_b32_e32 v124, 64, v162
	v_add_u32_e32 v124, 64, v124
	v_add_u32_e32 v135, 0x400, v131
	v_add_u32_e32 v137, 0x600, v131
	v_add_u32_e32 v139, 0x2010, v131
	v_add_u32_e32 v190, 0x2210, v131
	v_add_u32_e32 v191, 0x2410, v131
	v_add_u32_e32 v133, 8, v133
	v_add_u32_e32 v192, 0x2610, v131
	s_waitcnt vmcnt(0)
	s_nop 0
	v_mov_b32_e32 v148, v92
	v_mov_b32_e32 v149, v84
	v_mov_b32_e32 v186, v64
	v_mov_b32_e32 v187, v48
	v_mov_b32_e32 v144, v93
	v_mov_b32_e32 v145, v85
	v_pk_mul_f32 v[148:149], v[148:149], v[148:149]
	v_mov_b32_e32 v182, v65
	v_mov_b32_e32 v183, v49
	v_pk_mul_f32 v[186:187], v[186:187], v[186:187]
	v_mov_b32_e32 v146, v94
	v_mov_b32_e32 v147, v86
	v_pk_fma_f32 v[144:145], v[144:145], v[144:145], v[148:149]
	v_mov_b32_e32 v150, v56
	v_mov_b32_e32 v151, v76
	v_mov_b32_e32 v184, v66
	v_mov_b32_e32 v185, v50
	v_pk_fma_f32 v[182:183], v[182:183], v[182:183], v[186:187]
	v_mov_b32_e32 v188, v24
	v_mov_b32_e32 v189, v36
	v_pk_fma_f32 v[144:145], v[146:147], v[146:147], v[144:145]
	v_mov_b32_e32 v146, v57
	v_mov_b32_e32 v147, v77
	v_pk_mul_f32 v[150:151], v[150:151], v[150:151]
	v_pk_fma_f32 v[182:183], v[184:185], v[184:185], v[182:183]
	v_mov_b32_e32 v184, v25
	v_mov_b32_e32 v185, v37
	v_pk_mul_f32 v[188:189], v[188:189], v[188:189]
	v_mov_b32_e32 v142, v95
	v_mov_b32_e32 v143, v87
	v_mov_b32_e32 v148, v58
	v_mov_b32_e32 v149, v78
	v_pk_fma_f32 v[146:147], v[146:147], v[146:147], v[150:151]
	v_mov_b32_e32 v154, v67
	v_mov_b32_e32 v155, v51
	v_mov_b32_e32 v186, v26
	v_mov_b32_e32 v187, v38
	v_pk_fma_f32 v[184:185], v[184:185], v[184:185], v[188:189]
	v_pk_fma_f32 v[142:143], v[142:143], v[142:143], v[144:145]
	v_mov_b32_e32 v144, v59
	v_mov_b32_e32 v145, v79
	v_pk_fma_f32 v[146:147], v[148:149], v[148:149], v[146:147]
	v_pk_fma_f32 v[154:155], v[154:155], v[154:155], v[182:183]
	v_mov_b32_e32 v182, v27
	v_mov_b32_e32 v183, v39
	v_pk_fma_f32 v[184:185], v[186:187], v[186:187], v[184:185]
	v_pk_fma_f32 v[144:145], v[144:145], v[144:145], v[146:147]
	v_xor_b32_e32 v146, 1, v162
	v_pk_fma_f32 v[182:183], v[182:183], v[182:183], v[184:185]
	v_mov_b32_e32 v184, v154
	v_mov_b32_e32 v185, v142
	v_mov_b32_e32 v142, v155
	v_cmp_lt_i32_e64 s[0:1], v146, v124
	v_pk_add_f32 v[142:143], v[184:185], v[142:143]
	v_mov_b32_e32 v154, v183
	v_mov_b32_e32 v155, v145
	v_cndmask_b32_e64 v146, v162, v146, s[0:1]
	v_pk_add_f32 v[142:143], v[154:155], v[142:143]
	v_mov_b32_e32 v183, v144
	v_lshlrev_b32_e32 v193, 2, v146
	v_pk_add_f32 v[142:143], v[182:183], v[142:143]
	ds_bpermute_b32 v145, v193, v143
	ds_bpermute_b32 v144, v193, v142
	v_xor_b32_e32 v146, 2, v162
	v_cmp_lt_i32_e64 s[0:1], v146, v124
	v_pk_mov_b32 v[152:153], v[56:57], v[58:59] op_sel:[1,0]
	v_pk_add_f32 v[96:97], v[96:97], 1.0 op_sel_hi:[1,0]
	v_cndmask_b32_e64 v146, v162, v146, s[0:1]
	v_lshlrev_b32_e32 v194, 2, v146
	s_waitcnt lgkmcnt(0)
	v_pk_add_f32 v[142:143], v[142:143], v[144:145]
	ds_bpermute_b32 v145, v194, v143
	ds_bpermute_b32 v144, v194, v142
	v_xor_b32_e32 v146, 4, v162
	v_cmp_lt_i32_e64 s[0:1], v146, v124
	v_pk_add_f32 v[98:99], v[98:99], 1.0 op_sel_hi:[1,0]
	v_pk_mov_b32 v[148:149], v[84:85], v[86:87] op_sel:[1,0]
	v_cndmask_b32_e64 v146, v162, v146, s[0:1]
	v_lshlrev_b32_e32 v195, 2, v146
	s_waitcnt lgkmcnt(0)
	v_pk_add_f32 v[142:143], v[142:143], v[144:145]
	ds_bpermute_b32 v145, v195, v143
	ds_bpermute_b32 v144, v195, v142
	v_xor_b32_e32 v146, 8, v162
	v_cmp_lt_i32_e64 s[0:1], v146, v124
	v_mov_b32_e32 v85, v148
	v_mov_b32_e32 v86, v149
	v_cndmask_b32_e64 v146, v162, v146, s[0:1]
	v_lshlrev_b32_e32 v196, 2, v146
	s_waitcnt lgkmcnt(0)
	v_pk_add_f32 v[142:143], v[142:143], v[144:145]
	ds_bpermute_b32 v145, v196, v143
	ds_bpermute_b32 v144, v196, v142
	v_xor_b32_e32 v146, 16, v162
	v_cmp_lt_i32_e64 s[0:1], v146, v124
	v_pk_mov_b32 v[150:151], v[76:77], v[78:79] op_sel:[1,0]
	v_pk_add_f32 v[100:101], v[100:101], 1.0 op_sel_hi:[1,0]
	v_cndmask_b32_e64 v146, v162, v146, s[0:1]
	v_lshlrev_b32_e32 v197, 2, v146
	s_waitcnt lgkmcnt(0)
	v_pk_add_f32 v[142:143], v[142:143], v[144:145]
	ds_bpermute_b32 v145, v197, v143
	ds_bpermute_b32 v144, v197, v142
	v_xor_b32_e32 v146, 32, v162
	v_cmp_lt_i32_e64 s[0:1], v146, v124
	v_pk_add_f32 v[102:103], v[102:103], 1.0 op_sel_hi:[1,0]
	v_pk_add_f32 v[104:105], v[104:105], 1.0 op_sel_hi:[1,0]
	v_cndmask_b32_e64 v124, v162, v146, s[0:1]
	v_lshlrev_b32_e32 v124, 2, v124
	s_waitcnt lgkmcnt(0)
	v_pk_add_f32 v[142:143], v[142:143], v[144:145]
	ds_bpermute_b32 v145, v124, v143
	ds_bpermute_b32 v144, v124, v142
	v_pk_mov_b32 v[146:147], v[92:93], v[94:95] op_sel:[1,0]
	v_pk_add_f32 v[106:107], v[106:107], 1.0 op_sel_hi:[1,0]
	v_mov_b32_e32 v93, v146
	v_mov_b32_e32 v94, v147
	s_waitcnt lgkmcnt(0)
	v_pk_add_f32 v[142:143], v[142:143], v[144:145]
	v_pk_add_f32 v[108:109], v[108:109], 1.0 op_sel_hi:[1,0]
	v_pk_fma_f32 v[142:143], v[142:143], s[20:21], v[126:127] op_sel_hi:[1,0,0]
	v_pk_add_f32 v[110:111], v[110:111], 1.0 op_sel_hi:[1,0]
	v_mul_f32_e32 v57, 0x4b800000, v143
	v_cmp_gt_f32_e64 s[4:5], s68, v143
	v_cmp_gt_f32_e64 s[0:1], s68, v142
	v_pk_add_f32 v[44:45], v[44:45], 1.0 op_sel_hi:[1,0]
	v_cndmask_b32_e64 v57, v143, v57, s[4:5]
	v_rsq_f32_e32 v57, v57
	v_pk_add_f32 v[46:47], v[46:47], 1.0 op_sel_hi:[1,0]
	v_pk_add_f32 v[32:33], v[32:33], 1.0 op_sel_hi:[1,0]
	v_pk_add_f32 v[34:35], v[34:35], 1.0 op_sel_hi:[1,0]
	v_mul_f32_e32 v58, 0x45800000, v57
	v_cndmask_b32_e64 v124, v57, v58, s[4:5]
	v_pk_mul_f32 v[92:93], v[92:93], v[124:125] op_sel_hi:[1,0]
	v_pk_mul_f32 v[94:95], v[94:95], v[124:125] op_sel_hi:[1,0]
	v_pk_mul_f32 v[92:93], v[8:9], v[92:93]
	v_pk_mul_f32 v[94:95], v[10:11], v[94:95]
	v_pk_fma_f32 v[88:89], v[96:97], v[92:93], v[88:89]
	v_pk_fma_f32 v[90:91], v[98:99], v[94:95], v[90:91]
	v_bfe_u32 v77, v89, 16, 1
	v_bfe_u32 v57, v91, 16, 1
	v_bfe_u32 v58, v90, 16, 1
	v_bfe_u32 v78, v88, 16, 1
	v_pk_mul_f32 v[84:85], v[84:85], v[124:125] op_sel_hi:[1,0]
	v_pk_mul_f32 v[86:87], v[86:87], v[124:125] op_sel_hi:[1,0]
	v_add3_u32 v78, v88, v78, s33
	v_add3_u32 v77, v89, v77, s33
	v_add3_u32 v58, v90, v58, s33
	v_add3_u32 v57, v91, v57, s33
	v_pk_mul_f32 v[86:87], v[2:3], v[86:87]
	v_pk_mul_f32 v[84:85], v[0:1], v[84:85]
	v_perm_b32 v57, v57, v58, s69
	v_perm_b32 v58, v77, v78, s69
	v_pk_fma_f32 v[80:81], v[100:101], v[84:85], v[80:81]
	v_pk_fma_f32 v[82:83], v[102:103], v[86:87], v[82:83]
	ds_write2_b32 v131, v58, v57 offset1:1
	v_bfe_u32 v57, v83, 16, 1
	v_bfe_u32 v58, v82, 16, 1
	v_bfe_u32 v77, v81, 16, 1
	v_bfe_u32 v78, v80, 16, 1
	v_add3_u32 v78, v80, v78, s33
	v_add3_u32 v77, v81, v77, s33
	v_add3_u32 v58, v82, v58, s33
	v_add3_u32 v57, v83, v57, s33
	v_perm_b32 v57, v57, v58, s69
	v_perm_b32 v58, v77, v78, s69
	v_mov_b32_e32 v77, v150
	v_mov_b32_e32 v78, v151
	v_pk_mul_f32 v[76:77], v[76:77], v[124:125] op_sel_hi:[1,0]
	v_pk_mul_f32 v[78:79], v[78:79], v[124:125] op_sel_hi:[1,0]
	v_pk_mul_f32 v[76:77], v[4:5], v[76:77]
	v_pk_mul_f32 v[78:79], v[6:7], v[78:79]
	v_pk_fma_f32 v[72:73], v[104:105], v[76:77], v[72:73]
	v_pk_fma_f32 v[74:75], v[106:107], v[78:79], v[74:75]
	ds_write2_b32 v131, v58, v57 offset0:128 offset1:129
	v_bfe_u32 v57, v75, 16, 1
	v_bfe_u32 v58, v74, 16, 1
	v_bfe_u32 v76, v73, 16, 1
	v_bfe_u32 v77, v72, 16, 1
	v_add3_u32 v72, v72, v77, s33
	v_add3_u32 v73, v73, v76, s33
	v_add3_u32 v58, v74, v58, s33
	v_add3_u32 v57, v75, v57, s33
	v_perm_b32 v57, v57, v58, s69
	v_perm_b32 v58, v73, v72, s69
	ds_write2_b32 v135, v58, v57 offset1:1
	v_mov_b32_e32 v57, v152
	v_mov_b32_e32 v58, v153
	v_pk_mul_f32 v[56:57], v[56:57], v[124:125] op_sel_hi:[1,0]
	v_pk_mul_f32 v[58:59], v[58:59], v[124:125] op_sel_hi:[1,0]
	v_pk_mul_f32 v[56:57], v[12:13], v[56:57]
	v_pk_mul_f32 v[58:59], v[14:15], v[58:59]
	v_pk_fma_f32 v[52:53], v[108:109], v[56:57], v[52:53]
	v_pk_fma_f32 v[54:55], v[110:111], v[58:59], v[54:55]
	v_bfe_u32 v58, v53, 16, 1
	v_bfe_u32 v56, v55, 16, 1
	v_bfe_u32 v57, v54, 16, 1
	v_bfe_u32 v59, v52, 16, 1
	v_add3_u32 v52, v52, v59, s33
	v_add3_u32 v53, v53, v58, s33
	v_add3_u32 v54, v54, v57, s33
	v_add3_u32 v55, v55, v56, s33
	v_perm_b32 v54, v55, v54, s69
	v_perm_b32 v52, v53, v52, s69
	ds_write2_b32 v137, v52, v54 offset1:1
	v_mul_f32_e32 v52, 0x4b800000, v142
	v_cndmask_b32_e64 v52, v142, v52, s[0:1]
	v_rsq_f32_e32 v52, v52
	v_pk_mov_b32 v[54:55], v[64:65], v[66:67] op_sel:[1,0]
	v_pk_add_f32 v[58:59], v[68:69], 1.0 op_sel_hi:[1,0]
	v_mov_b32_e32 v65, v54
	v_mul_f32_e32 v53, 0x45800000, v52
	v_cndmask_b32_e64 v52, v52, v53, s[0:1]
	v_mov_b32_e32 v66, v55
	v_pk_mul_f32 v[56:57], v[64:65], v[52:53] op_sel_hi:[1,0]
	v_pk_mul_f32 v[54:55], v[66:67], v[52:53] op_sel_hi:[1,0]
	v_pk_mul_f32 v[56:57], v[8:9], v[56:57]
	v_pk_mul_f32 v[54:55], v[10:11], v[54:55]
	v_pk_add_f32 v[64:65], v[70:71], 1.0 op_sel_hi:[1,0]
	v_pk_fma_f32 v[56:57], v[58:59], v[56:57], v[60:61]
	v_pk_fma_f32 v[54:55], v[64:65], v[54:55], v[62:63]
	v_bfe_u32 v59, v57, 16, 1
	v_bfe_u32 v53, v55, 16, 1
	v_bfe_u32 v58, v54, 16, 1
	v_bfe_u32 v60, v56, 16, 1
	v_add3_u32 v56, v56, v60, s33
	v_add3_u32 v57, v57, v59, s33
	v_add3_u32 v54, v54, v58, s33
	v_add3_u32 v53, v55, v53, s33
	v_perm_b32 v53, v53, v54, s69
	v_perm_b32 v54, v57, v56, s69
	ds_write2_b32 v139, v54, v53 offset1:1
	v_pk_mov_b32 v[54:55], v[48:49], v[50:51] op_sel:[1,0]
	v_pk_add_f32 v[20:21], v[20:21], 1.0 op_sel_hi:[1,0]
	v_mov_b32_e32 v49, v54
	v_mov_b32_e32 v50, v55
	v_pk_mul_f32 v[48:49], v[48:49], v[52:53] op_sel_hi:[1,0]
	v_pk_mul_f32 v[50:51], v[50:51], v[52:53] op_sel_hi:[1,0]
	v_pk_mul_f32 v[48:49], v[0:1], v[48:49]
	v_pk_mul_f32 v[50:51], v[2:3], v[50:51]
	v_pk_fma_f32 v[40:41], v[44:45], v[48:49], v[40:41]
	v_pk_fma_f32 v[42:43], v[46:47], v[50:51], v[42:43]
	v_bfe_u32 v46, v41, 16, 1
	v_bfe_u32 v44, v43, 16, 1
	v_bfe_u32 v45, v42, 16, 1
	v_bfe_u32 v47, v40, 16, 1
	v_add3_u32 v40, v40, v47, s33
	v_add3_u32 v41, v41, v46, s33
	v_add3_u32 v42, v42, v45, s33
	v_add3_u32 v43, v43, v44, s33
	v_perm_b32 v42, v43, v42, s69
	v_perm_b32 v40, v41, v40, s69
	ds_write2_b32 v190, v40, v42 offset1:1
	v_pk_mov_b32 v[40:41], v[36:37], v[38:39] op_sel:[1,0]
	v_pk_add_f32 v[22:23], v[22:23], 1.0 op_sel_hi:[1,0]
	v_mov_b32_e32 v37, v40
	v_mov_b32_e32 v38, v41
	v_pk_mul_f32 v[36:37], v[36:37], v[52:53] op_sel_hi:[1,0]
	v_pk_mul_f32 v[38:39], v[38:39], v[52:53] op_sel_hi:[1,0]
	v_pk_mul_f32 v[36:37], v[4:5], v[36:37]
	v_pk_mul_f32 v[38:39], v[6:7], v[38:39]
	v_pk_fma_f32 v[28:29], v[32:33], v[36:37], v[28:29]
	v_pk_fma_f32 v[30:31], v[34:35], v[38:39], v[30:31]
	v_bfe_u32 v34, v29, 16, 1
	v_bfe_u32 v32, v31, 16, 1
	v_bfe_u32 v33, v30, 16, 1
	v_bfe_u32 v35, v28, 16, 1
	v_add3_u32 v28, v28, v35, s33
	v_add3_u32 v29, v29, v34, s33
	v_add3_u32 v30, v30, v33, s33
	v_add3_u32 v31, v31, v32, s33
	v_perm_b32 v30, v31, v30, s69
	v_perm_b32 v28, v29, v28, s69
	ds_write2_b32 v191, v28, v30 offset1:1
	v_pk_mov_b32 v[28:29], v[24:25], v[26:27] op_sel:[1,0]
	s_mov_b64 s[0:1], 0x8000
	v_mov_b32_e32 v25, v28
	v_mov_b32_e32 v26, v29
	v_pk_mul_f32 v[24:25], v[24:25], v[52:53] op_sel_hi:[1,0]
	v_pk_mul_f32 v[26:27], v[26:27], v[52:53] op_sel_hi:[1,0]
	v_pk_mul_f32 v[24:25], v[12:13], v[24:25]
	v_pk_mul_f32 v[26:27], v[14:15], v[26:27]
	v_pk_fma_f32 v[16:17], v[20:21], v[24:25], v[16:17]
	v_pk_fma_f32 v[18:19], v[22:23], v[26:27], v[18:19]
	v_bfe_u32 v22, v17, 16, 1
	v_bfe_u32 v20, v19, 16, 1
	v_bfe_u32 v21, v18, 16, 1
	v_bfe_u32 v23, v16, 16, 1
	v_add3_u32 v16, v16, v23, s33
	v_add3_u32 v17, v17, v22, s33
	v_add3_u32 v18, v18, v21, s33
	v_add3_u32 v19, v19, v20, s33
	v_lshl_add_u64 v[140:141], v[140:141], 0, s[0:1]
	v_cmp_lt_i32_e64 s[0:1], 7, v133
	v_perm_b32 v18, v19, v18, s69
	v_perm_b32 v16, v17, v16, s69
	v_add_u32_e32 v131, 0x4020, v131
	s_or_b64 s[10:11], s[0:1], s[10:11]
	ds_write2_b32 v192, v16, v18 offset1:1
	s_andn2_b64 exec, exec, s[10:11]
	s_cbranch_execnz .LBB0_1405
.LBB0_1406:
	s_or_b64 exec, exec, s[8:9]
	s_lshl_b32 s1, s19, 4
	s_cmpk_lt_i32 s19, 0x100
	s_mov_b32 s0, 0x7ffffc00
	s_cselect_b32 s0, 0xffffff00, s0
	s_movk_i32 s4, 0xf0
	s_cselect_b32 s4, s4, 0x3f0
	s_cselect_b32 s5, 8, 10
	s_and_b32 s0, s0, s1
	s_and_b32 s4, s4, s1
	s_ashr_i32 s1, s0, 31
	s_lshl_b64 s[0:1], s[0:1], 11
	s_add_u32 s0, s14, s0
	s_addc_u32 s1, s15, s1
	s_lshl_b32 s4, s4, 1
	s_add_u32 s0, s0, s4
	s_addc_u32 s1, s1, 0
	v_lshlrev_b64 v[16:17], s5, v[114:115]
	v_lshlrev_b64 v[18:19], s5, v[116:117]
	s_waitcnt vmcnt(10)
	v_lshlrev_b64 v[20:21], s5, v[118:119]
	v_lshlrev_b64 v[22:23], s5, v[120:121]
	v_lshl_add_u64 v[16:17], v[16:17], 1, s[0:1]
	v_lshl_add_u64 v[18:19], v[18:19], 1, s[0:1]
	v_lshl_add_u64 v[20:21], v[20:21], 1, s[0:1]
	v_lshl_add_u64 v[22:23], v[22:23], 1, s[0:1]
	s_mov_b32 s0, 0
	s_movk_i32 s1, 0x804
	s_waitcnt lgkmcnt(0)
	s_barrier
	s_waitcnt vmcnt(0)
.LBB0_1407:
	v_add_u32_e32 v32, s0, v123
	v_ashrrev_i32_e32 v24, 7, v32
	v_and_b32_e32 v28, -8, v24
	v_mad_u64_u32 v[30:31], s[4:5], v28, s1, v[122:123]
	ds_read_u16 v24, v30
	ds_read_u16 v25, v30 offset:2052
	s_addk_i32 s0, 0x400
	s_cmpk_eq_i32 s0, 0x800
	s_waitcnt lgkmcnt(0)
	v_lshl_or_b32 v24, v25, 16, v24
	ds_read_u16 v25, v30 offset:4104
	ds_read_u16 v26, v30 offset:6156
	s_waitcnt lgkmcnt(0)
	v_lshl_or_b32 v25, v26, 16, v25
	ds_read_u16 v26, v30 offset:8208
	ds_read_u16 v27, v30 offset:10260
	s_waitcnt lgkmcnt(0)
	v_lshl_or_b32 v26, v27, 16, v26
	ds_read_u16 v27, v30 offset:12312
	ds_read_u16 v29, v30 offset:14364
	s_waitcnt lgkmcnt(0)
	v_lshl_or_b32 v27, v29, 16, v27
	v_ashrrev_i32_e32 v29, 31, v28
	v_lshl_add_u64 v[28:29], v[28:29], 1, v[16:17]
	global_store_dwordx4 v[28:29], v[24:27], off
	s_nop 1
	v_add_u32_e32 v24, 0x100, v32
	v_ashrrev_i32_e32 v24, 7, v24
	v_and_b32_e32 v28, -8, v24
	v_mad_u64_u32 v[30:31], s[4:5], v28, s1, v[130:131]
	ds_read_u16 v24, v30
	ds_read_u16 v25, v30 offset:2052
	s_waitcnt lgkmcnt(0)
	v_lshl_or_b32 v24, v25, 16, v24
	ds_read_u16 v25, v30 offset:4104
	ds_read_u16 v26, v30 offset:6156
	s_waitcnt lgkmcnt(0)
	v_lshl_or_b32 v25, v26, 16, v25
	ds_read_u16 v26, v30 offset:8208
	ds_read_u16 v27, v30 offset:10260
	s_waitcnt lgkmcnt(0)
	v_lshl_or_b32 v26, v27, 16, v26
	ds_read_u16 v27, v30 offset:12312
	ds_read_u16 v29, v30 offset:14364
	s_waitcnt lgkmcnt(0)
	v_lshl_or_b32 v27, v29, 16, v27
	v_ashrrev_i32_e32 v29, 31, v28
	v_lshl_add_u64 v[28:29], v[28:29], 1, v[18:19]
	global_store_dwordx4 v[28:29], v[24:27], off
	s_nop 1
	v_add_u32_e32 v24, 0x200, v32
	v_ashrrev_i32_e32 v24, 7, v24
	v_and_b32_e32 v28, -8, v24
	v_mad_u64_u32 v[30:31], s[4:5], v28, s1, v[132:133]
	ds_read_u16 v24, v30
	ds_read_u16 v25, v30 offset:2052
	s_waitcnt lgkmcnt(0)
	v_lshl_or_b32 v24, v25, 16, v24
	ds_read_u16 v25, v30 offset:4104
	ds_read_u16 v26, v30 offset:6156
	s_waitcnt lgkmcnt(0)
	v_lshl_or_b32 v25, v26, 16, v25
	ds_read_u16 v26, v30 offset:8208
	ds_read_u16 v27, v30 offset:10260
	s_waitcnt lgkmcnt(0)
	v_lshl_or_b32 v26, v27, 16, v26
	ds_read_u16 v27, v30 offset:12312
	ds_read_u16 v29, v30 offset:14364
	s_waitcnt lgkmcnt(0)
	v_lshl_or_b32 v27, v29, 16, v27
	v_ashrrev_i32_e32 v29, 31, v28
	v_lshl_add_u64 v[28:29], v[28:29], 1, v[20:21]
	global_store_dwordx4 v[28:29], v[24:27], off
	s_nop 1
	v_add_u32_e32 v24, 0x300, v32
	v_ashrrev_i32_e32 v24, 7, v24
	v_and_b32_e32 v28, -8, v24
	v_mad_u64_u32 v[30:31], s[4:5], v28, s1, v[134:135]
	ds_read_u16 v24, v30
	ds_read_u16 v25, v30 offset:2052
	s_waitcnt lgkmcnt(0)
	v_lshl_or_b32 v24, v25, 16, v24
	ds_read_u16 v25, v30 offset:4104
	ds_read_u16 v26, v30 offset:6156
	s_waitcnt lgkmcnt(0)
	v_lshl_or_b32 v25, v26, 16, v25
	ds_read_u16 v26, v30 offset:8208
	ds_read_u16 v27, v30 offset:10260
	s_waitcnt lgkmcnt(0)
	v_lshl_or_b32 v26, v27, 16, v26
	ds_read_u16 v27, v30 offset:12312
	ds_read_u16 v29, v30 offset:14364
	s_waitcnt lgkmcnt(0)
	v_lshl_or_b32 v27, v29, 16, v27
	v_ashrrev_i32_e32 v29, 31, v28
	v_lshl_add_u64 v[28:29], v[28:29], 1, v[22:23]
	global_store_dwordx4 v[28:29], v[24:27], off
	s_cbranch_scc0 .LBB0_1407
	v_readlane_b32 s0, v239, 30
	s_add_i32 s19, s19, s76
	s_add_i32 s18, s18, s0
	s_cmpk_gt_i32 s19, 0x17f
	v_add_u32_e32 v136, s0, v136
	s_barrier
	s_cbranch_scc0 .LBB0_1403
